# residual-gate GEMM epilogue: 16 residual-row loads hoisted to the epilogue top (one wait) instead of load->vmcnt(0)->compute->store per 8 elements
# speedup vs baseline: 1.0313x; 1.0159x over previous
; __device__ __forceinline__ unsigned cvt_pk_bf16(float lo, float hi) { unsigned r; asm volatile("v_cvt_pk_bf16_f32 %0, %1, %2" : "=v"(r) : "v"(lo), "v"(hi)); return r; }
;     __device__ __forceinline__ void operator()(const f32x4 (&acc)[2][2][4][2], const Unit& u, int wr, int wc, int fr, int fq) const {
;         const int row0 = u.pm * BM + wr * 64 + fr, col0 = u.pn * BM + wc * 32 + 8 * fq; const float* gp = gate + (size_t)(u.pm >> 3) * gstride + col0;
;         f32x4 gv[2][2];
; #pragma unroll
;         for (int bj = 0; bj < 2; ++bj)
; #pragma unroll
;             for (int n = 0; n < 2; ++n) gv[bj][n] = *(const f32x4*)(gp + bj * HALF + 4 * n);
; #pragma unroll
;         for (int ai = 0; ai < 2; ++ai)
; #pragma unroll
;             for (int m = 0; m < 4; ++m) { const size_t off = (size_t)(row0 + ai * HALF + m * 16) * ldc + col0;
; #pragma unroll
;                 for (int bj = 0; bj < 2; ++bj) { const u32x4 bw = *(const u32x4*)(base + off + bj * HALF);
;                     const f32x4 a0 = acc[ai][bj][m][0], a1 = acc[ai][bj][m][1], g0 = gv[bj][0], g1 = gv[bj][1];
;                     u32x4 w;
;                     w.x = cvt_pk_bf16(__uint_as_float(bw.x << 16) + g0[0] * a0[0], __uint_as_float(bw.x & 0xffff0000u) + g0[1] * a0[1]);
;                     w.y = cvt_pk_bf16(__uint_as_float(bw.y << 16) + g0[2] * a0[2], __uint_as_float(bw.y & 0xffff0000u) + g0[3] * a0[3]);
;                     w.z = cvt_pk_bf16(__uint_as_float(bw.z << 16) + g1[0] * a1[0], __uint_as_float(bw.z & 0xffff0000u) + g1[1] * a1[1]);
;                     w.w = cvt_pk_bf16(__uint_as_float(bw.w << 16) + g1[2] * a1[2], __uint_as_float(bw.w & 0xffff0000u) + g1[3] * a1[3]);
;                     *(u32x4*)(out + off + bj * HALF) = w; } }
.LBB0_182:
	v_lshl_add_u32 v162, s45, 8, v1
	v_lshl_or_b32 v160, s46, 8, v168
	v_ashrrev_i32_e32 v163, 31, v162
	v_ashrrev_i32_e32 v161, 31, v160
	v_lshlrev_b64 v[106:107], 11, v[162:163]
	v_lshl_add_u64 v[106:107], v[106:107], 0, v[160:161]
	v_lshlrev_b64 v[158:159], 1, v[106:107]
	s_ashr_i32 s24, s45, 3
	v_lshl_add_u64 v[174:175], s[10:11], 0, v[158:159]
	s_mul_hi_i32 s25, s24, 0xc000
	s_mul_i32 s24, s24, 0xc000
	global_load_dwordx4 v[170:173], v[174:175], off
	s_add_u32 s24, s37, s24
	s_addc_u32 s25, s38, s25
	v_lshl_add_u64 v[110:111], v[160:161], 2, s[24:25]
	global_load_dwordx4 v[134:137], v[110:111], off
	global_load_dwordx4 v[130:133], v[110:111], off offset:16
	global_load_dwordx4 v[106:109], v[110:111], off offset:528
	s_nop 0
	global_load_dwordx4 v[110:113], v[110:111], off offset:512
	global_load_dwordx4 v[182:185], v[174:175], off offset:256
	s_mov_b64 s[24:25], 0x10000
	v_lshl_add_u64 v[218:219], v[174:175], 0, s[24:25]
	global_load_dwordx4 v[186:189], v[218:219], off
	global_load_dwordx4 v[190:193], v[218:219], off offset:256
	s_mov_b64 s[24:25], 0x20000
	v_lshl_add_u64 v[218:219], v[174:175], 0, s[24:25]
	global_load_dwordx4 v[194:197], v[218:219], off
	global_load_dwordx4 v[198:201], v[218:219], off offset:256
	s_mov_b64 s[24:25], 0x30000
	v_lshl_add_u64 v[218:219], v[174:175], 0, s[24:25]
	global_load_dwordx4 v[202:205], v[218:219], off
	global_load_dwordx4 v[206:209], v[218:219], off offset:256
	s_mov_b64 s[24:25], 0x80000
	v_lshl_add_u64 v[218:219], v[174:175], 0, s[24:25]
	global_load_dwordx4 v[210:213], v[218:219], off
	global_load_dwordx4 v[226:229], v[218:219], off offset:256
	s_mov_b64 s[24:25], 0x90000
	v_lshl_add_u64 v[218:219], v[174:175], 0, s[24:25]
	global_load_dwordx4 v[230:233], v[218:219], off
	global_load_dwordx4 v[234:237], v[218:219], off offset:256
	s_mov_b64 s[24:25], 0xa0000
	v_lshl_add_u64 v[218:219], v[174:175], 0, s[24:25]
	global_load_dwordx4 v[238:241], v[218:219], off
	global_load_dwordx4 v[242:245], v[218:219], off offset:256
	s_mov_b64 s[24:25], 0xb0000
	v_lshl_add_u64 v[218:219], v[174:175], 0, s[24:25]
	global_load_dwordx4 v[246:249], v[218:219], off
	global_load_dwordx4 v[250:253], v[218:219], off offset:256
	v_lshl_add_u64 v[176:177], s[16:17], 0, v[158:159]
	s_mov_b64 s[24:25], 0x80000
	s_and_b64 vcc, exec, s[6:7]
	s_mov_b64 s[6:7], -1
	s_waitcnt vmcnt(0)
	v_lshlrev_b32_e32 v163, 16, v170
	v_and_b32_e32 v170, 0xffff0000, v170
	v_lshlrev_b32_e32 v178, 16, v171
	v_and_b32_e32 v171, 0xffff0000, v171
	v_lshlrev_b32_e32 v179, 16, v172
	v_and_b32_e32 v172, 0xffff0000, v172
	v_lshlrev_b32_e32 v180, 16, v173
	v_and_b32_e32 v173, 0xffff0000, v173
	v_fmac_f32_e32 v163, v142, v134
	v_fmac_f32_e32 v170, v143, v135
	v_fmac_f32_e32 v178, v144, v136
	v_fmac_f32_e32 v171, v145, v137
	v_fmac_f32_e32 v179, v138, v130
	v_fmac_f32_e32 v172, v139, v131
	v_fmac_f32_e32 v180, v140, v132
	v_fmac_f32_e32 v173, v141, v133
	v_cvt_pk_bf16_f32 v138, v163, v170
	v_cvt_pk_bf16_f32 v139, v178, v171
	v_cvt_pk_bf16_f32 v140, v179, v172
	v_cvt_pk_bf16_f32 v141, v180, v173
	global_store_dwordx4 v[176:177], v[138:141], off
	v_or_b32_e32 v142, 16, v162
	v_ashrrev_i32_e32 v143, 31, v142
	v_lshlrev_b64 v[142:143], 11, v[142:143]
	v_lshl_add_u64 v[142:143], v[142:143], 0, v[160:161]
	v_lshlrev_b64 v[142:143], 1, v[142:143]
	v_lshl_add_u64 v[144:145], s[10:11], 0, v[142:143]
	s_nop 1
	v_lshlrev_b32_e32 v163, 16, v182
	v_and_b32_e32 v138, 0xffff0000, v182
	v_lshlrev_b32_e32 v170, 16, v183
	v_and_b32_e32 v139, 0xffff0000, v183
	v_lshlrev_b32_e32 v171, 16, v184
	v_and_b32_e32 v140, 0xffff0000, v184
	v_lshlrev_b32_e32 v172, 16, v185
	v_and_b32_e32 v141, 0xffff0000, v185
	v_fmac_f32_e32 v163, v126, v110
	v_fmac_f32_e32 v138, v127, v111
	v_fmac_f32_e32 v170, v128, v112
	v_fmac_f32_e32 v139, v129, v113
	v_fmac_f32_e32 v171, v122, v106
	v_fmac_f32_e32 v140, v123, v107
	v_fmac_f32_e32 v172, v124, v108
	v_fmac_f32_e32 v141, v125, v109
	v_cvt_pk_bf16_f32 v122, v163, v138
	v_cvt_pk_bf16_f32 v123, v170, v139
	v_cvt_pk_bf16_f32 v124, v171, v140
	v_cvt_pk_bf16_f32 v125, v172, v141
	global_store_dwordx4 v[176:177], v[122:125], off offset:256
	v_lshl_add_u64 v[126:127], s[16:17], 0, v[142:143]
	s_nop 1
	v_lshlrev_b32_e32 v128, 16, v186
	v_and_b32_e32 v122, 0xffff0000, v186
	v_lshlrev_b32_e32 v129, 16, v187
	v_and_b32_e32 v123, 0xffff0000, v187
	v_lshlrev_b32_e32 v138, 16, v188
	v_and_b32_e32 v124, 0xffff0000, v188
	v_lshlrev_b32_e32 v139, 16, v189
	v_and_b32_e32 v125, 0xffff0000, v189
	v_fmac_f32_e32 v128, v118, v134
	v_fmac_f32_e32 v122, v119, v135
	v_fmac_f32_e32 v129, v120, v136
	v_fmac_f32_e32 v123, v121, v137
	v_fmac_f32_e32 v138, v114, v130
	v_fmac_f32_e32 v124, v115, v131
	v_fmac_f32_e32 v139, v116, v132
	v_fmac_f32_e32 v125, v117, v133
	v_cvt_pk_bf16_f32 v114, v128, v122
	v_cvt_pk_bf16_f32 v115, v129, v123
	v_cvt_pk_bf16_f32 v116, v138, v124
	v_cvt_pk_bf16_f32 v117, v139, v125
	global_store_dwordx4 v[126:127], v[114:117], off
	v_or_b32_e32 v118, 32, v162
	v_ashrrev_i32_e32 v119, 31, v118
	v_lshlrev_b64 v[118:119], 11, v[118:119]
	v_lshl_add_u64 v[118:119], v[118:119], 0, v[160:161]
	v_lshlrev_b64 v[118:119], 1, v[118:119]
	v_lshl_add_u64 v[120:121], s[10:11], 0, v[118:119]
	s_nop 1
	v_lshlrev_b32_e32 v122, 16, v190
	v_and_b32_e32 v114, 0xffff0000, v190
	v_lshlrev_b32_e32 v123, 16, v191
	v_and_b32_e32 v115, 0xffff0000, v191
	v_lshlrev_b32_e32 v124, 16, v192
	v_and_b32_e32 v116, 0xffff0000, v192
	v_lshlrev_b32_e32 v125, 16, v193
	v_and_b32_e32 v117, 0xffff0000, v193
	v_fmac_f32_e32 v122, v102, v110
	v_fmac_f32_e32 v114, v103, v111
	v_fmac_f32_e32 v123, v104, v112
	v_fmac_f32_e32 v115, v105, v113
	v_fmac_f32_e32 v124, v98, v106
; __device__ __forceinline__ unsigned cvt_pk_bf16(float lo, float hi) { unsigned r; asm volatile("v_cvt_pk_bf16_f32 %0, %1, %2" : "=v"(r) : "v"(lo), "v"(hi)); return r; }
;     __device__ __forceinline__ void operator()(const f32x4 (&acc)[2][2][4][2], const Unit& u, int wr, int wc, int fr, int fq) const {
;     ...
;         for (int ai = 0; ai < 2; ++ai)
; #pragma unroll
;             for (int m = 0; m < 4; ++m) { const size_t off = (size_t)(row0 + ai * HALF + m * 16) * ldc + col0;
; #pragma unroll
;                 for (int bj = 0; bj < 2; ++bj) { const u32x4 bw = *(const u32x4*)(base + off + bj * HALF);
;                     const f32x4 a0 = acc[ai][bj][m][0], a1 = acc[ai][bj][m][1], g0 = gv[bj][0], g1 = gv[bj][1];
;                     u32x4 w;
;                     w.x = cvt_pk_bf16(__uint_as_float(bw.x << 16) + g0[0] * a0[0], __uint_as_float(bw.x & 0xffff0000u) + g0[1] * a0[1]);
;                     w.y = cvt_pk_bf16(__uint_as_float(bw.y << 16) + g0[2] * a0[2], __uint_as_float(bw.y & 0xffff0000u) + g0[3] * a0[3]);
;                     w.z = cvt_pk_bf16(__uint_as_float(bw.z << 16) + g1[0] * a1[0], __uint_as_float(bw.z & 0xffff0000u) + g1[1] * a1[1]);
;                     w.w = cvt_pk_bf16(__uint_as_float(bw.w << 16) + g1[2] * a1[2], __uint_as_float(bw.w & 0xffff0000u) + g1[3] * a1[3]);
;                     *(u32x4*)(out + off + bj * HALF) = w; } }
	v_fmac_f32_e32 v116, v99, v107
	v_fmac_f32_e32 v125, v100, v108
	v_fmac_f32_e32 v117, v101, v109
	v_cvt_pk_bf16_f32 v98, v122, v114
	v_cvt_pk_bf16_f32 v99, v123, v115
	v_cvt_pk_bf16_f32 v100, v124, v116
	v_cvt_pk_bf16_f32 v101, v125, v117
	global_store_dwordx4 v[126:127], v[98:101], off offset:256
	v_lshl_add_u64 v[102:103], s[16:17], 0, v[118:119]
	s_nop 1
	v_lshlrev_b32_e32 v104, 16, v194
	v_and_b32_e32 v98, 0xffff0000, v194
	v_lshlrev_b32_e32 v105, 16, v195
	v_and_b32_e32 v99, 0xffff0000, v195
	v_lshlrev_b32_e32 v114, 16, v196
	v_and_b32_e32 v100, 0xffff0000, v196
	v_lshlrev_b32_e32 v115, 16, v197
	v_and_b32_e32 v101, 0xffff0000, v197
	v_fmac_f32_e32 v104, v94, v134
	v_fmac_f32_e32 v98, v95, v135
	v_fmac_f32_e32 v105, v96, v136
	v_fmac_f32_e32 v99, v97, v137
	v_fmac_f32_e32 v114, v90, v130
	v_fmac_f32_e32 v100, v91, v131
	v_fmac_f32_e32 v115, v92, v132
	v_fmac_f32_e32 v101, v93, v133
	v_cvt_pk_bf16_f32 v90, v104, v98
	v_cvt_pk_bf16_f32 v91, v105, v99
	v_cvt_pk_bf16_f32 v92, v114, v100
	v_cvt_pk_bf16_f32 v93, v115, v101
	global_store_dwordx4 v[102:103], v[90:93], off
	v_or_b32_e32 v94, 48, v162
	v_ashrrev_i32_e32 v95, 31, v94
	v_lshlrev_b64 v[94:95], 11, v[94:95]
	v_lshl_add_u64 v[94:95], v[94:95], 0, v[160:161]
	v_lshlrev_b64 v[94:95], 1, v[94:95]
	v_lshl_add_u64 v[96:97], s[10:11], 0, v[94:95]
	s_nop 1
	v_lshlrev_b32_e32 v98, 16, v198
	v_and_b32_e32 v90, 0xffff0000, v198
	v_lshlrev_b32_e32 v99, 16, v199
	v_and_b32_e32 v91, 0xffff0000, v199
	v_lshlrev_b32_e32 v100, 16, v200
	v_and_b32_e32 v92, 0xffff0000, v200
	v_lshlrev_b32_e32 v101, 16, v201
	v_and_b32_e32 v93, 0xffff0000, v201
	v_fmac_f32_e32 v98, v86, v110
	v_fmac_f32_e32 v90, v87, v111
	v_fmac_f32_e32 v99, v88, v112
	v_fmac_f32_e32 v91, v89, v113
	v_fmac_f32_e32 v100, v82, v106
	v_fmac_f32_e32 v92, v83, v107
	v_fmac_f32_e32 v101, v84, v108
	v_fmac_f32_e32 v93, v85, v109
	v_cvt_pk_bf16_f32 v82, v98, v90
	v_cvt_pk_bf16_f32 v83, v99, v91
	v_cvt_pk_bf16_f32 v84, v100, v92
	v_cvt_pk_bf16_f32 v85, v101, v93
	global_store_dwordx4 v[102:103], v[82:85], off offset:256
	v_lshl_add_u64 v[86:87], s[16:17], 0, v[94:95]
	s_nop 1
	v_lshlrev_b32_e32 v88, 16, v202
	v_and_b32_e32 v82, 0xffff0000, v202
	v_lshlrev_b32_e32 v89, 16, v203
	v_and_b32_e32 v83, 0xffff0000, v203
	v_lshlrev_b32_e32 v90, 16, v204
	v_and_b32_e32 v84, 0xffff0000, v204
	v_lshlrev_b32_e32 v91, 16, v205
	v_and_b32_e32 v85, 0xffff0000, v205
	v_fmac_f32_e32 v88, v78, v134
	v_fmac_f32_e32 v82, v79, v135
	v_fmac_f32_e32 v89, v80, v136
	v_fmac_f32_e32 v83, v81, v137
	v_fmac_f32_e32 v90, v74, v130
	v_fmac_f32_e32 v84, v75, v131
	v_fmac_f32_e32 v91, v76, v132
	v_fmac_f32_e32 v85, v77, v133
	v_cvt_pk_bf16_f32 v74, v88, v82
	v_cvt_pk_bf16_f32 v75, v89, v83
	v_cvt_pk_bf16_f32 v76, v90, v84
	v_cvt_pk_bf16_f32 v77, v91, v85
	global_store_dwordx4 v[86:87], v[74:77], off
	v_lshl_add_u64 v[78:79], v[158:159], 0, s[24:25]
	v_lshl_add_u64 v[80:81], s[10:11], 0, v[78:79]
	s_mov_b64 s[24:25], 0x90000
	s_nop 1
	v_lshlrev_b32_e32 v82, 16, v206
	v_and_b32_e32 v74, 0xffff0000, v206
	v_lshlrev_b32_e32 v83, 16, v207
	v_and_b32_e32 v75, 0xffff0000, v207
	v_lshlrev_b32_e32 v84, 16, v208
	v_and_b32_e32 v76, 0xffff0000, v208
	v_lshlrev_b32_e32 v85, 16, v209
	v_and_b32_e32 v77, 0xffff0000, v209
	v_fmac_f32_e32 v82, v70, v110
	v_fmac_f32_e32 v74, v71, v111
	v_fmac_f32_e32 v83, v72, v112
	v_fmac_f32_e32 v75, v73, v113
	v_fmac_f32_e32 v84, v66, v106
	v_fmac_f32_e32 v76, v67, v107
	v_fmac_f32_e32 v85, v68, v108
	v_fmac_f32_e32 v77, v69, v109
	v_cvt_pk_bf16_f32 v66, v82, v74
	v_cvt_pk_bf16_f32 v67, v83, v75
	v_cvt_pk_bf16_f32 v68, v84, v76
	v_cvt_pk_bf16_f32 v69, v85, v77
	global_store_dwordx4 v[86:87], v[66:69], off offset:256
	v_lshl_add_u64 v[70:71], s[16:17], 0, v[78:79]
	s_nop 1
	v_lshlrev_b32_e32 v72, 16, v210
	v_and_b32_e32 v66, 0xffff0000, v210
	v_lshlrev_b32_e32 v73, 16, v211
	v_and_b32_e32 v67, 0xffff0000, v211
	v_lshlrev_b32_e32 v74, 16, v212
	v_and_b32_e32 v68, 0xffff0000, v212
	v_lshlrev_b32_e32 v75, 16, v213
	v_and_b32_e32 v69, 0xffff0000, v213
	v_fmac_f32_e32 v72, v62, v134
	v_fmac_f32_e32 v66, v63, v135
	v_fmac_f32_e32 v73, v64, v136
	v_fmac_f32_e32 v67, v65, v137
	v_fmac_f32_e32 v74, v58, v130
	v_fmac_f32_e32 v68, v59, v131
	v_fmac_f32_e32 v75, v60, v132
	v_fmac_f32_e32 v69, v61, v133
	v_cvt_pk_bf16_f32 v58, v72, v66
	v_cvt_pk_bf16_f32 v59, v73, v67
	v_cvt_pk_bf16_f32 v60, v74, v68
	v_cvt_pk_bf16_f32 v61, v75, v69
	global_store_dwordx4 v[70:71], v[58:61], off
	v_lshl_add_u64 v[62:63], v[158:159], 0, s[24:25]
	v_lshl_add_u64 v[64:65], s[10:11], 0, v[62:63]
	s_mov_b64 s[24:25], 0xa0000
	s_nop 1
	v_lshlrev_b32_e32 v66, 16, v226
	v_and_b32_e32 v58, 0xffff0000, v226
	v_lshlrev_b32_e32 v67, 16, v227
	v_and_b32_e32 v59, 0xffff0000, v227
	v_lshlrev_b32_e32 v68, 16, v228
	v_and_b32_e32 v60, 0xffff0000, v228
	v_lshlrev_b32_e32 v69, 16, v229
	v_and_b32_e32 v61, 0xffff0000, v229
	v_fmac_f32_e32 v66, v54, v110
	v_fmac_f32_e32 v58, v55, v111
	v_fmac_f32_e32 v67, v56, v112
	v_fmac_f32_e32 v59, v57, v113
	v_fmac_f32_e32 v68, v50, v106
	v_fmac_f32_e32 v60, v51, v107
; __device__ __forceinline__ unsigned cvt_pk_bf16(float lo, float hi) { unsigned r; asm volatile("v_cvt_pk_bf16_f32 %0, %1, %2" : "=v"(r) : "v"(lo), "v"(hi)); return r; }
; #define PG8_BAR __builtin_amdgcn_s_barrier()
; template <class Epi, class Sched, bool ALIGN_EPI = false, bool SP2 = false>
; __device__ __forceinline__ void gemm_phase(PG8_LAS unsigned char* lds, const Gemm g, const Sched& S, const Epi& E) {
;     ...
;         if (!has_next) break;
; #pragma unroll
;         for (int a = 0; a < 2; ++a)
; #pragma unroll
;             for (int b = 0; b < 2; ++b)
; #pragma unroll
;                 for (int m = 0; m < 4; ++m)
; #pragma unroll
;                     for (int n = 0; n < 2; ++n) acc[a][b][m][n] = (f32x4){0.f, 0.f, 0.f, 0.f};
;         cur = nxt; cA = nA; cB = nB; ++ui;
;         if constexpr (ALIGN_EPI) { if (wr == 1) PG8_BAR; }
;     __device__ __forceinline__ void operator()(const f32x4 (&acc)[2][2][4][2], const Unit& u, int wr, int wc, int fr, int fq) const {
;     ...
;         for (int ai = 0; ai < 2; ++ai)
; #pragma unroll
;             for (int m = 0; m < 4; ++m) { const size_t off = (size_t)(row0 + ai * HALF + m * 16) * ldc + col0;
; #pragma unroll
;                 for (int bj = 0; bj < 2; ++bj) { const u32x4 bw = *(const u32x4*)(base + off + bj * HALF);
;                     const f32x4 a0 = acc[ai][bj][m][0], a1 = acc[ai][bj][m][1], g0 = gv[bj][0], g1 = gv[bj][1];
;                     u32x4 w;
;                     w.x = cvt_pk_bf16(__uint_as_float(bw.x << 16) + g0[0] * a0[0], __uint_as_float(bw.x & 0xffff0000u) + g0[1] * a0[1]);
;                     w.y = cvt_pk_bf16(__uint_as_float(bw.y << 16) + g0[2] * a0[2], __uint_as_float(bw.y & 0xffff0000u) + g0[3] * a0[3]);
;                     w.z = cvt_pk_bf16(__uint_as_float(bw.z << 16) + g1[0] * a1[0], __uint_as_float(bw.z & 0xffff0000u) + g1[1] * a1[1]);
;                     w.w = cvt_pk_bf16(__uint_as_float(bw.w << 16) + g1[2] * a1[2], __uint_as_float(bw.w & 0xffff0000u) + g1[3] * a1[3]);
;                     *(u32x4*)(out + off + bj * HALF) = w; } }
	v_fmac_f32_e32 v69, v52, v108
	v_fmac_f32_e32 v61, v53, v109
	v_cvt_pk_bf16_f32 v50, v66, v58
	v_cvt_pk_bf16_f32 v51, v67, v59
	v_cvt_pk_bf16_f32 v52, v68, v60
	v_cvt_pk_bf16_f32 v53, v69, v61
	global_store_dwordx4 v[70:71], v[50:53], off offset:256
	v_lshl_add_u64 v[54:55], s[16:17], 0, v[62:63]
	s_nop 1
	v_lshlrev_b32_e32 v56, 16, v230
	v_and_b32_e32 v50, 0xffff0000, v230
	v_lshlrev_b32_e32 v57, 16, v231
	v_and_b32_e32 v51, 0xffff0000, v231
	v_lshlrev_b32_e32 v58, 16, v232
	v_and_b32_e32 v52, 0xffff0000, v232
	v_lshlrev_b32_e32 v59, 16, v233
	v_and_b32_e32 v53, 0xffff0000, v233
	v_fmac_f32_e32 v56, v46, v134
	v_fmac_f32_e32 v50, v47, v135
	v_fmac_f32_e32 v57, v48, v136
	v_fmac_f32_e32 v51, v49, v137
	v_fmac_f32_e32 v58, v42, v130
	v_fmac_f32_e32 v52, v43, v131
	v_fmac_f32_e32 v59, v44, v132
	v_fmac_f32_e32 v53, v45, v133
	v_cvt_pk_bf16_f32 v42, v56, v50
	v_cvt_pk_bf16_f32 v43, v57, v51
	v_cvt_pk_bf16_f32 v44, v58, v52
	v_cvt_pk_bf16_f32 v45, v59, v53
	global_store_dwordx4 v[54:55], v[42:45], off
	v_lshl_add_u64 v[46:47], v[158:159], 0, s[24:25]
	v_lshl_add_u64 v[48:49], s[10:11], 0, v[46:47]
	s_mov_b64 s[24:25], 0xb0000
	s_nop 1
	v_lshlrev_b32_e32 v50, 16, v234
	v_and_b32_e32 v42, 0xffff0000, v234
	v_lshlrev_b32_e32 v51, 16, v235
	v_and_b32_e32 v43, 0xffff0000, v235
	v_lshlrev_b32_e32 v52, 16, v236
	v_and_b32_e32 v44, 0xffff0000, v236
	v_lshlrev_b32_e32 v53, 16, v237
	v_and_b32_e32 v45, 0xffff0000, v237
	v_fmac_f32_e32 v50, v38, v110
	v_fmac_f32_e32 v42, v39, v111
	v_fmac_f32_e32 v51, v40, v112
	v_fmac_f32_e32 v43, v41, v113
	v_fmac_f32_e32 v52, v34, v106
	v_fmac_f32_e32 v44, v35, v107
	v_fmac_f32_e32 v53, v36, v108
	v_fmac_f32_e32 v45, v37, v109
	v_cvt_pk_bf16_f32 v34, v50, v42
	v_cvt_pk_bf16_f32 v35, v51, v43
	v_cvt_pk_bf16_f32 v36, v52, v44
	v_cvt_pk_bf16_f32 v37, v53, v45
	global_store_dwordx4 v[54:55], v[34:37], off offset:256
	v_lshl_add_u64 v[38:39], s[16:17], 0, v[46:47]
	s_nop 1
	v_lshlrev_b32_e32 v40, 16, v238
	v_and_b32_e32 v34, 0xffff0000, v238
	v_lshlrev_b32_e32 v41, 16, v239
	v_and_b32_e32 v35, 0xffff0000, v239
	v_lshlrev_b32_e32 v42, 16, v240
	v_and_b32_e32 v36, 0xffff0000, v240
	v_lshlrev_b32_e32 v43, 16, v241
	v_and_b32_e32 v37, 0xffff0000, v241
	v_fmac_f32_e32 v40, v30, v134
	v_fmac_f32_e32 v34, v31, v135
	v_fmac_f32_e32 v41, v32, v136
	v_fmac_f32_e32 v35, v33, v137
	v_fmac_f32_e32 v42, v26, v130
	v_fmac_f32_e32 v36, v27, v131
	v_fmac_f32_e32 v43, v28, v132
	v_fmac_f32_e32 v37, v29, v133
	v_cvt_pk_bf16_f32 v26, v40, v34
	v_cvt_pk_bf16_f32 v27, v41, v35
	v_cvt_pk_bf16_f32 v28, v42, v36
	v_cvt_pk_bf16_f32 v29, v43, v37
	global_store_dwordx4 v[38:39], v[26:29], off
	v_lshl_add_u64 v[30:31], v[158:159], 0, s[24:25]
	v_lshl_add_u64 v[32:33], s[10:11], 0, v[30:31]
	s_nop 1
	v_lshlrev_b32_e32 v34, 16, v242
	v_and_b32_e32 v26, 0xffff0000, v242
	v_lshlrev_b32_e32 v35, 16, v243
	v_and_b32_e32 v27, 0xffff0000, v243
	v_lshlrev_b32_e32 v36, 16, v244
	v_and_b32_e32 v28, 0xffff0000, v244
	v_lshlrev_b32_e32 v37, 16, v245
	v_and_b32_e32 v29, 0xffff0000, v245
	v_fmac_f32_e32 v34, v22, v110
	v_fmac_f32_e32 v26, v23, v111
	v_fmac_f32_e32 v35, v24, v112
	v_fmac_f32_e32 v27, v25, v113
	v_fmac_f32_e32 v36, v18, v106
	v_fmac_f32_e32 v28, v19, v107
	v_fmac_f32_e32 v37, v20, v108
	v_fmac_f32_e32 v29, v21, v109
	v_cvt_pk_bf16_f32 v18, v34, v26
	v_cvt_pk_bf16_f32 v19, v35, v27
	v_cvt_pk_bf16_f32 v20, v36, v28
	v_cvt_pk_bf16_f32 v21, v37, v29
	global_store_dwordx4 v[38:39], v[18:21], off offset:256
	v_lshl_add_u64 v[22:23], s[16:17], 0, v[30:31]
	s_nop 1
	v_lshlrev_b32_e32 v24, 16, v246
	v_and_b32_e32 v18, 0xffff0000, v246
	v_lshlrev_b32_e32 v25, 16, v247
	v_and_b32_e32 v19, 0xffff0000, v247
	v_lshlrev_b32_e32 v26, 16, v248
	v_and_b32_e32 v20, 0xffff0000, v248
	v_lshlrev_b32_e32 v27, 16, v249
	v_and_b32_e32 v21, 0xffff0000, v249
	v_fmac_f32_e32 v24, v14, v134
	v_fmac_f32_e32 v18, v15, v135
	v_fmac_f32_e32 v25, v16, v136
	v_fmac_f32_e32 v19, v17, v137
	v_fmac_f32_e32 v26, v10, v130
	v_fmac_f32_e32 v20, v11, v131
	v_fmac_f32_e32 v27, v12, v132
	v_fmac_f32_e32 v21, v13, v133
	v_cvt_pk_bf16_f32 v10, v24, v18
	v_cvt_pk_bf16_f32 v11, v25, v19
	v_cvt_pk_bf16_f32 v12, v26, v20
	v_cvt_pk_bf16_f32 v13, v27, v21
	global_store_dwordx4 v[22:23], v[10:13], off
	s_nop 1
	v_lshlrev_b32_e32 v14, 16, v250
	v_and_b32_e32 v10, 0xffff0000, v250
	v_lshlrev_b32_e32 v15, 16, v251
	v_and_b32_e32 v11, 0xffff0000, v251
	v_lshlrev_b32_e32 v16, 16, v252
	v_and_b32_e32 v12, 0xffff0000, v252
	v_lshlrev_b32_e32 v17, 16, v253
	v_and_b32_e32 v13, 0xffff0000, v253
	v_fmac_f32_e32 v14, v6, v110
	v_fmac_f32_e32 v10, v7, v111
	v_fmac_f32_e32 v15, v8, v112
	v_fmac_f32_e32 v11, v9, v113
	v_fmac_f32_e32 v16, v2, v106
	v_fmac_f32_e32 v12, v3, v107
	v_fmac_f32_e32 v17, v4, v108
	v_fmac_f32_e32 v13, v5, v109
	v_cvt_pk_bf16_f32 v2, v14, v10
	v_cvt_pk_bf16_f32 v3, v15, v11
	v_cvt_pk_bf16_f32 v4, v16, v12
	v_cvt_pk_bf16_f32 v5, v17, v13
	global_store_dwordx4 v[22:23], v[2:5], off offset:256
	s_cbranch_vccnz .LBB0_167
	s_andn2_b64 vcc, exec, s[18:19]
	s_cbranch_vccnz .LBB0_166
	s_barrier
	s_branch .LBB0_166
